# baseline (speedup 1.0000x reference)
; __device__ __forceinline__ float bf_lo(u32 v) { return __uint_as_float(v << 16); }
; __device__ __forceinline__ float bf_hi(u32 v) { return __uint_as_float(v & 0xffff0000u); }
; template <bool FOX>
; __device__ __forceinline__ void attn_pair(const Params& p, int it, char* smem, const int wv) {
;     ...
;     {
;       const int tid3 = opaque_tid(wv);
;       const int e_lane = tid3 & 63, e_fr = e_lane & 15, e_fq = e_lane >> 4, e_qw = q0 + wv * 32;
;       #pragma unroll
;       for (int qt = 0; qt < 2; ++qt) {
;         const float inv = FOX ? 1.0f / st1[qt] : 1.0f;
;         u16* yrow = Yp + (tok0 + e_qw + qt * 16 + e_fr) * ld + e_fq * 4;
;         #pragma unroll
;         for (int dt = 0; dt < 8; ++dt) {
;           uint2 g = *(const uint2*)(yrow + dt * 16);
;           uint2 pk;
;           pk.x = pack2(o[dt][qt][0] * inv * bf_lo(g.x), o[dt][qt][1] * inv * bf_hi(g.x));
;           pk.y = pack2(o[dt][qt][2] * inv * bf_lo(g.y), o[dt][qt][3] * inv * bf_hi(g.y));
;           *(uint2*)(yrow + dt * 16) = pk;
;         }
;       }
;     }
.LBB0_332:
	v_mbcnt_lo_u32_b32 v120, -1, 0
	v_mbcnt_hi_u32_b32 v120, -1, v120
	v_and_b32_e32 v120, 16, v120
	v_lshrrev_b32_e32 v121, 1, v120
	v_add_u32_e32 v120, v120, v121
	v_mov_b32_e32 v121, 0
	v_readlane_b32 s0, v255, 38
	s_lshl_b32 s0, s0, 1
	v_readlane_b32 s1, v255, 31
	s_barrier
	v_mbcnt_lo_u32_b32 v44, -1, 0
	v_mbcnt_hi_u32_b32 v44, -1, v44
	v_readlane_b32 s2, v255, 39
	s_add_u32 s0, s1, s0
	v_readlane_b32 s1, v255, 32
	v_and_or_b32 v46, v44, 15, s2
	v_lshrrev_b32_e32 v44, 1, v44
	s_addc_u32 s1, s1, 0
	v_and_b32_e32 v140, 24, v44
	v_lshl_add_u64 v[44:45], s[0:1], 0, v[140:141]
	s_movk_i32 s13, 0x5000
	v_mad_u64_u32 v[44:45], s[0:1], v46, s13, v[44:45]
	v_readlane_b32 s0, v255, 40
	s_mov_b32 s16, 0x50000
	v_add_co_u32_e32 v46, vcc, s16, v44
	v_mad_i32_i24 v45, s0, v152, v45
	v_lshl_add_u64 v[168:169], v[44:45], 0, v[120:121]
	global_load_dwordx4 v[124:127], v[168:169], off
	global_load_dwordx4 v[128:131], v[168:169], off offset:64
	global_load_dwordx4 v[132:135], v[168:169], off offset:128
	global_load_dwordx4 v[136:139], v[168:169], off offset:192
	v_addc_co_u32_e32 v47, vcc, 0, v45, vcc
	v_lshl_add_u64 v[170:171], v[46:47], 0, v[120:121]
	global_load_dwordx4 v[144:147], v[170:171], off
	global_load_dwordx4 v[148:151], v[170:171], off offset:64
	global_load_dwordx4 v[156:159], v[170:171], off offset:128
	global_load_dwordx4 v[164:167], v[170:171], off offset:192
	v_readlane_b32 s68, v255, 11
	v_readlane_b32 s92, v255, 35
	v_readlane_b32 s14, v255, 41
	v_readlane_b32 s70, v255, 13
	v_readlane_b32 s71, v255, 14
	v_readlane_b32 s91, v255, 15
	v_readlane_b32 s93, v255, 36
	v_readlane_b32 s95, v255, 37
	v_readlane_b32 s15, v255, 42
	v_readlane_b32 s69, v255, 12
	s_waitcnt vmcnt(7)
	v_permlane16_swap_b32_e32 v124, v126
	v_permlane16_swap_b32_e32 v125, v127
	v_mov_b32_e32 v48, v124
	v_mov_b32_e32 v49, v125
	v_mov_b32_e32 v50, v126
	v_mov_b32_e32 v51, v127
	v_lshlrev_b32_e32 v100, 16, v48
	v_and_b32_e32 v101, 0xffff0000, v48
	v_lshlrev_b32_e32 v48, 16, v49
	v_and_b32_e32 v49, 0xffff0000, v49
	s_waitcnt vmcnt(7)
	v_lshlrev_b32_e32 v102, 16, v50
	v_and_b32_e32 v103, 0xffff0000, v50
	v_lshlrev_b32_e32 v50, 16, v51
	v_and_b32_e32 v51, 0xffff0000, v51
	s_waitcnt vmcnt(6)
	v_permlane16_swap_b32_e32 v128, v130
	v_permlane16_swap_b32_e32 v129, v131
	v_mov_b32_e32 v72, v128
	v_mov_b32_e32 v73, v129
	v_mov_b32_e32 v74, v130
	v_mov_b32_e32 v75, v131
	v_lshlrev_b32_e32 v104, 16, v72
	v_and_b32_e32 v105, 0xffff0000, v72
	v_lshlrev_b32_e32 v72, 16, v73
	v_and_b32_e32 v73, 0xffff0000, v73
	s_waitcnt vmcnt(6)
	v_lshlrev_b32_e32 v106, 16, v74
	v_and_b32_e32 v107, 0xffff0000, v74
	v_lshlrev_b32_e32 v74, 16, v75
	v_and_b32_e32 v75, 0xffff0000, v75
	s_waitcnt vmcnt(5)
	v_permlane16_swap_b32_e32 v132, v134
	v_permlane16_swap_b32_e32 v133, v135
	v_mov_b32_e32 v76, v132
	v_mov_b32_e32 v77, v133
	v_mov_b32_e32 v78, v134
	v_mov_b32_e32 v79, v135
	v_lshlrev_b32_e32 v108, 16, v76
	v_and_b32_e32 v109, 0xffff0000, v76
	v_lshlrev_b32_e32 v76, 16, v77
	v_and_b32_e32 v77, 0xffff0000, v77
	s_waitcnt vmcnt(5)
	v_lshlrev_b32_e32 v110, 16, v78
	v_and_b32_e32 v111, 0xffff0000, v78
	v_lshlrev_b32_e32 v78, 16, v79
	v_and_b32_e32 v79, 0xffff0000, v79
	v_pk_mul_f32 v[40:41], v[40:41], v[100:101]
	v_pk_mul_f32 v[42:43], v[42:43], v[48:49]
	v_pk_mul_f32 v[48:49], v[68:69], v[102:103]
	v_pk_mul_f32 v[50:51], v[70:71], v[50:51]
	v_pk_mul_f32 v[64:65], v[64:65], v[104:105]
	v_pk_mul_f32 v[66:67], v[66:67], v[72:73]
	v_pk_mul_f32 v[60:61], v[60:61], v[106:107]
	v_pk_mul_f32 v[62:63], v[62:63], v[74:75]
	v_pk_mul_f32 v[56:57], v[56:57], v[108:109]
	v_pk_mul_f32 v[58:59], v[58:59], v[76:77]
	v_pk_mul_f32 v[52:53], v[52:53], v[110:111]
	v_pk_mul_f32 v[54:55], v[54:55], v[78:79]
	v_cvt_pk_bf16_f32 v40, v40, v41
	v_cvt_pk_bf16_f32 v41, v42, v43
	s_waitcnt vmcnt(4)
	v_permlane16_swap_b32_e32 v136, v138
	v_permlane16_swap_b32_e32 v137, v139
	v_mov_b32_e32 v80, v136
	v_mov_b32_e32 v81, v137
	v_mov_b32_e32 v82, v138
	v_mov_b32_e32 v83, v139
	v_lshlrev_b32_e32 v112, 16, v80
	v_and_b32_e32 v113, 0xffff0000, v80
	v_cvt_pk_bf16_f32 v42, v48, v49
	v_cvt_pk_bf16_f32 v43, v50, v51
	v_cvt_pk_bf16_f32 v48, v64, v65
	v_cvt_pk_bf16_f32 v49, v66, v67
	v_cvt_pk_bf16_f32 v50, v60, v61
	v_cvt_pk_bf16_f32 v51, v62, v63
	v_cvt_pk_bf16_f32 v56, v56, v57
	v_cvt_pk_bf16_f32 v57, v58, v59
	v_cvt_pk_bf16_f32 v52, v52, v53
	v_cvt_pk_bf16_f32 v53, v54, v55
	v_mov_b32_e32 v116, v40
	v_mov_b32_e32 v117, v41
	v_mov_b32_e32 v118, v42
	v_mov_b32_e32 v119, v43
	v_lshl_add_u64 v[122:123], v[44:45], 0, v[120:121]
	s_nop 0
	v_permlane16_swap_b32_e32 v116, v118
	v_permlane16_swap_b32_e32 v117, v119
	global_store_dwordx4 v[122:123], v[116:119], off
	s_nop 1
	v_mov_b32_e32 v116, v48
	v_mov_b32_e32 v117, v49
	v_mov_b32_e32 v118, v50
	v_mov_b32_e32 v119, v51
	v_lshl_add_u64 v[122:123], v[44:45], 0, v[120:121]
	s_nop 0
	v_permlane16_swap_b32_e32 v116, v118
	v_permlane16_swap_b32_e32 v117, v119
	global_store_dwordx4 v[122:123], v[116:119], off offset:64
	s_nop 1
	v_mov_b32_e32 v116, v56
	v_mov_b32_e32 v117, v57
	v_mov_b32_e32 v118, v52
	v_mov_b32_e32 v119, v53
	v_lshl_add_u64 v[122:123], v[44:45], 0, v[120:121]
	s_nop 0
	v_permlane16_swap_b32_e32 v116, v118
	v_permlane16_swap_b32_e32 v117, v119
	global_store_dwordx4 v[122:123], v[116:119], off offset:128
	s_nop 1
	v_lshlrev_b32_e32 v40, 16, v81
	v_and_b32_e32 v41, 0xffff0000, v81
	v_pk_mul_f32 v[36:37], v[36:37], v[112:113]
	v_pk_mul_f32 v[38:39], v[38:39], v[40:41]
	v_cvt_pk_bf16_f32 v36, v36, v37
	v_cvt_pk_bf16_f32 v37, v38, v39
	v_mov_b32_e32 v116, v36
	v_mov_b32_e32 v117, v37
	s_waitcnt vmcnt(7)
; __device__ __forceinline__ float bf_lo(u32 v) { return __uint_as_float(v << 16); }
; __device__ __forceinline__ float bf_hi(u32 v) { return __uint_as_float(v & 0xffff0000u); }
; template <bool FOX>
; __device__ __forceinline__ void attn_pair(const Params& p, int it, char* smem, const int wv) {
;     ...
;       #pragma unroll
;       for (int qt = 0; qt < 2; ++qt) {
;         const float inv = FOX ? 1.0f / st1[qt] : 1.0f;
;         u16* yrow = Yp + (tok0 + e_qw + qt * 16 + e_fr) * ld + e_fq * 4;
;         #pragma unroll
;         for (int dt = 0; dt < 8; ++dt) {
;           uint2 g = *(const uint2*)(yrow + dt * 16);
;           uint2 pk;
;           pk.x = pack2(o[dt][qt][0] * inv * bf_lo(g.x), o[dt][qt][1] * inv * bf_hi(g.x));
;           pk.y = pack2(o[dt][qt][2] * inv * bf_lo(g.y), o[dt][qt][3] * inv * bf_hi(g.y));
;           *(uint2*)(yrow + dt * 16) = pk;
;         }
;       }
	v_lshlrev_b32_e32 v36, 16, v82
	v_and_b32_e32 v37, 0xffff0000, v82
	v_pk_mul_f32 v[32:33], v[32:33], v[36:37]
	v_lshlrev_b32_e32 v36, 16, v83
	v_and_b32_e32 v37, 0xffff0000, v83
	v_pk_mul_f32 v[34:35], v[34:35], v[36:37]
	v_cvt_pk_bf16_f32 v32, v32, v33
	v_cvt_pk_bf16_f32 v33, v34, v35
	v_mov_b32_e32 v118, v32
	v_mov_b32_e32 v119, v33
	v_lshl_add_u64 v[122:123], v[44:45], 0, v[120:121]
	s_nop 0
	v_permlane16_swap_b32_e32 v116, v118
	v_permlane16_swap_b32_e32 v117, v119
	global_store_dwordx4 v[122:123], v[116:119], off offset:192
	s_nop 1
	s_waitcnt vmcnt(7)
	v_permlane16_swap_b32_e32 v144, v146
	v_permlane16_swap_b32_e32 v145, v147
	v_mov_b32_e32 v84, v144
	v_mov_b32_e32 v85, v145
	v_mov_b32_e32 v86, v146
	v_mov_b32_e32 v87, v147
	v_lshlrev_b32_e32 v32, 16, v84
	v_and_b32_e32 v33, 0xffff0000, v84
	v_pk_mul_f32 v[28:29], v[28:29], v[32:33]
	v_lshlrev_b32_e32 v32, 16, v85
	v_and_b32_e32 v33, 0xffff0000, v85
	v_pk_mul_f32 v[30:31], v[30:31], v[32:33]
	v_cvt_pk_bf16_f32 v28, v28, v29
	v_cvt_pk_bf16_f32 v29, v30, v31
	v_mov_b32_e32 v116, v28
	v_mov_b32_e32 v117, v29
	s_waitcnt vmcnt(7)
	v_lshlrev_b32_e32 v28, 16, v86
	v_and_b32_e32 v29, 0xffff0000, v86
	v_pk_mul_f32 v[24:25], v[24:25], v[28:29]
	v_lshlrev_b32_e32 v28, 16, v87
	v_and_b32_e32 v29, 0xffff0000, v87
	v_pk_mul_f32 v[26:27], v[26:27], v[28:29]
	v_cvt_pk_bf16_f32 v24, v24, v25
	v_cvt_pk_bf16_f32 v25, v26, v27
	v_mov_b32_e32 v118, v24
	v_mov_b32_e32 v119, v25
	v_lshl_add_u64 v[122:123], v[46:47], 0, v[120:121]
	s_nop 0
	v_permlane16_swap_b32_e32 v116, v118
	v_permlane16_swap_b32_e32 v117, v119
	global_store_dwordx4 v[122:123], v[116:119], off
	s_nop 1
	s_waitcnt vmcnt(7)
	v_permlane16_swap_b32_e32 v148, v150
	v_permlane16_swap_b32_e32 v149, v151
	v_mov_b32_e32 v88, v148
	v_mov_b32_e32 v89, v149
	v_mov_b32_e32 v90, v150
	v_mov_b32_e32 v91, v151
	v_lshlrev_b32_e32 v24, 16, v88
	v_and_b32_e32 v25, 0xffff0000, v88
	v_pk_mul_f32 v[20:21], v[20:21], v[24:25]
	v_lshlrev_b32_e32 v24, 16, v89
	v_and_b32_e32 v25, 0xffff0000, v89
	v_pk_mul_f32 v[22:23], v[22:23], v[24:25]
	v_cvt_pk_bf16_f32 v20, v20, v21
	v_cvt_pk_bf16_f32 v21, v22, v23
	v_mov_b32_e32 v116, v20
	v_mov_b32_e32 v117, v21
	s_waitcnt vmcnt(7)
	v_lshlrev_b32_e32 v20, 16, v90
	v_and_b32_e32 v21, 0xffff0000, v90
	v_pk_mul_f32 v[16:17], v[16:17], v[20:21]
	v_lshlrev_b32_e32 v20, 16, v91
	v_and_b32_e32 v21, 0xffff0000, v91
	v_pk_mul_f32 v[18:19], v[18:19], v[20:21]
	v_cvt_pk_bf16_f32 v16, v16, v17
	v_cvt_pk_bf16_f32 v17, v18, v19
	v_mov_b32_e32 v118, v16
	v_mov_b32_e32 v119, v17
	v_lshl_add_u64 v[122:123], v[46:47], 0, v[120:121]
	s_nop 0
	v_permlane16_swap_b32_e32 v116, v118
	v_permlane16_swap_b32_e32 v117, v119
	global_store_dwordx4 v[122:123], v[116:119], off offset:64
	s_nop 1
	s_waitcnt vmcnt(7)
	v_permlane16_swap_b32_e32 v156, v158
	v_permlane16_swap_b32_e32 v157, v159
	v_mov_b32_e32 v92, v156
	v_mov_b32_e32 v93, v157
	v_mov_b32_e32 v94, v158
	v_mov_b32_e32 v95, v159
	v_lshlrev_b32_e32 v16, 16, v92
	v_and_b32_e32 v17, 0xffff0000, v92
	v_pk_mul_f32 v[12:13], v[12:13], v[16:17]
	v_lshlrev_b32_e32 v16, 16, v93
	v_and_b32_e32 v17, 0xffff0000, v93
	v_pk_mul_f32 v[14:15], v[14:15], v[16:17]
	v_cvt_pk_bf16_f32 v12, v12, v13
	v_cvt_pk_bf16_f32 v13, v14, v15
	v_mov_b32_e32 v116, v12
	v_mov_b32_e32 v117, v13
	s_waitcnt vmcnt(7)
	v_lshlrev_b32_e32 v12, 16, v94
	v_and_b32_e32 v13, 0xffff0000, v94
	v_pk_mul_f32 v[8:9], v[8:9], v[12:13]
	v_lshlrev_b32_e32 v12, 16, v95
	v_and_b32_e32 v13, 0xffff0000, v95
	v_pk_mul_f32 v[10:11], v[10:11], v[12:13]
	v_cvt_pk_bf16_f32 v8, v8, v9
	v_cvt_pk_bf16_f32 v9, v10, v11
	v_mov_b32_e32 v118, v8
	v_mov_b32_e32 v119, v9
	v_lshl_add_u64 v[122:123], v[46:47], 0, v[120:121]
	s_nop 0
	v_permlane16_swap_b32_e32 v116, v118
	v_permlane16_swap_b32_e32 v117, v119
	global_store_dwordx4 v[122:123], v[116:119], off offset:128
	s_nop 1
	s_waitcnt vmcnt(7)
	v_permlane16_swap_b32_e32 v164, v166
	v_permlane16_swap_b32_e32 v165, v167
	v_mov_b32_e32 v96, v164
	v_mov_b32_e32 v97, v165
	v_mov_b32_e32 v98, v166
	v_mov_b32_e32 v99, v167
	v_lshlrev_b32_e32 v8, 16, v96
	v_and_b32_e32 v9, 0xffff0000, v96
	v_pk_mul_f32 v[4:5], v[4:5], v[8:9]
	v_lshlrev_b32_e32 v8, 16, v97
	v_and_b32_e32 v9, 0xffff0000, v97
	v_pk_mul_f32 v[6:7], v[6:7], v[8:9]
	v_cvt_pk_bf16_f32 v4, v4, v5
	v_cvt_pk_bf16_f32 v5, v6, v7
	v_mov_b32_e32 v116, v4
	v_mov_b32_e32 v117, v5
	s_waitcnt vmcnt(7)
	v_lshlrev_b32_e32 v4, 16, v98
	v_and_b32_e32 v5, 0xffff0000, v98
	v_pk_mul_f32 v[0:1], v[0:1], v[4:5]
	v_lshlrev_b32_e32 v4, 16, v99
	v_and_b32_e32 v5, 0xffff0000, v99
	v_pk_mul_f32 v[2:3], v[2:3], v[4:5]
	v_cvt_pk_bf16_f32 v0, v0, v1
	v_cvt_pk_bf16_f32 v1, v2, v3
	v_mov_b32_e32 v118, v0
	v_mov_b32_e32 v119, v1
	v_lshl_add_u64 v[122:123], v[46:47], 0, v[120:121]
	s_nop 0
	v_permlane16_swap_b32_e32 v116, v118
	v_permlane16_swap_b32_e32 v117, v119
	global_store_dwordx4 v[122:123], v[116:119], off offset:192
	s_nop 1
